# P8 (mixer post): v_rcp_f32 / v_sqrt_f32 in place of the IEEE division / sqrt expansions where the chains match
# baseline (speedup 1.0000x reference)
; __device__ __forceinline__ f32x4 unpack4(u32x2 u) { return (f32x4){__uint_as_float(u.x << 16), __uint_as_float(u.x & 0xffff0000u), __uint_as_float(u.y << 16), __uint_as_float(u.y & 0xffff0000u)}; }
; template <int ph>
; __device__ __forceinline__ void run_phase(const Args& args, LAS unsigned char* lds, const int G, const int bx, const bool fin = true) {
;     ...
;         for (int row = gw; row < MP; row += ngw) {
;             const int t = row & (T - 1); const int pbo = t > 0 ? -RP : 0; const float pm = t > 0 ? 1.f : 0.f;
;             POST_ROW(qr = unpack4(*(const u32x2*)(base + pbo)) * pm; qk = unpack4(*(const u32x2*)(base + pbo + 1024)) * pm; qv = unpack4(*(const u32x2*)(base + pbo + 2048)) * pm;)
.LBB0_1140:
	s_and_b32 s0, s42, 0x7ff
	v_lshl_add_u64 v[58:59], s[20:21], 0, v[56:57]
	s_cmp_eq_u32 s0, 0
	v_add_co_u32_e64 v90, s[0:1], s27, v58
	v_lshl_add_u64 v[64:65], s[24:25], 0, v[56:57]
	s_nop 0
	v_addc_co_u32_e64 v91, s[0:1], 0, v59, s[0:1]
	v_add_co_u32_e64 v86, s[0:1], s28, v58
	v_add_co_u32_e32 v60, vcc, 0x9e00000, v64
	s_nop 0
	v_addc_co_u32_e64 v87, s[0:1], 0, v59, s[0:1]
	v_add_co_u32_e64 v78, s[0:1], s38, v58
	v_addc_co_u32_e32 v61, vcc, 0, v65, vcc
	s_nop 0
	v_addc_co_u32_e64 v79, s[0:1], 0, v59, s[0:1]
	v_add_co_u32_e64 v80, s[0:1], s39, v58
	global_load_dwordx4 v[8:11], v[30:31], off
	global_load_dwordx4 v[12:15], v[32:33], off
	global_load_dwordx4 v[16:19], v[34:35], off
	v_addc_co_u32_e64 v81, s[0:1], 0, v59, s[0:1]
	v_add_co_u32_e64 v82, s[0:1], s40, v58
	global_load_dwordx4 v[24:27], v[36:37], off
	global_load_dwordx4 v[20:23], v[38:39], off
	global_load_dwordx4 v[0:3], v[40:41], off
	global_load_dwordx4 v[4:7], v[42:43], off
	v_addc_co_u32_e64 v83, s[0:1], 0, v59, s[0:1]
	v_add_co_u32_e64 v58, s[0:1], s41, v58
	global_load_dwordx2 v[76:77], v[90:91], off
	global_load_dwordx2 v[74:75], v[86:87], off
	global_load_dwordx2 v[72:73], v[78:79], off
	global_load_dwordx2 v[70:71], v[80:81], off
	global_load_dwordx2 v[68:69], v[82:83], off
	global_load_dwordx2 v[84:85], v[90:91], off offset:512
	global_load_dwordx2 v[88:89], v[86:87], off offset:512
	global_load_dwordx2 v[92:93], v[78:79], off offset:512
	global_load_dwordx2 v[94:95], v[80:81], off offset:512
	v_addc_co_u32_e64 v59, s[0:1], 0, v59, s[0:1]
	s_cselect_b64 s[0:1], -1, 0
	s_nop 0
	v_cndmask_b32_e64 v62, 1.0, 0, s[0:1]
	s_and_b64 s[0:1], s[0:1], exec
	global_load_dwordx2 v[96:97], v[82:83], off offset:512
	global_load_dwordx2 v[98:99], v[90:91], off offset:1024
	v_add_co_u32_e32 v66, vcc, s26, v64
	s_cselect_b32 s1, 0, -1
	s_cselect_b32 s0, 0, 0xffffe600
	global_load_dwordx2 v[112:113], v[90:91], off offset:1536
	s_nop 0
	global_load_dwordx2 v[90:91], v[86:87], off offset:1024
	s_nop 0
	global_load_dwordx2 v[86:87], v[86:87], off offset:1536
	s_nop 0
	global_load_dwordx2 v[114:115], v[78:79], off offset:1024
	global_load_dwordx2 v[134:135], v[78:79], off offset:1536
	global_load_dwordx2 v[136:137], v[80:81], off offset:1024
	global_load_dwordx2 v[140:141], v[80:81], off offset:1536
	global_load_dwordx2 v[142:143], v[82:83], off offset:1024
	global_load_dwordx2 v[144:145], v[82:83], off offset:1536
	v_addc_co_u32_e32 v67, vcc, 0, v65, vcc
	v_lshl_add_u64 v[64:65], v[64:65], 0, s[0:1]
	v_add_co_u32_e32 v78, vcc, s19, v64
	global_load_dwordx2 v[146:147], v[60:61], off
	global_load_dwordx2 v[148:149], v[60:61], off offset:2048
	v_addc_co_u32_e32 v79, vcc, 0, v65, vcc
	global_load_dwordx2 v[150:151], v[66:67], off
	global_load_dwordx2 v[152:153], v[78:79], off offset:2048
	v_add_co_u32_e32 v80, vcc, s26, v64
	s_add_i32 s42, s42, s18
	s_nop 0
	v_addc_co_u32_e32 v81, vcc, 0, v65, vcc
	global_load_dwordx2 v[154:155], v[80:81], off offset:-4096
	global_load_dwordx2 v[156:157], v[80:81], off
	s_add_u32 s20, s20, s22
	s_addc_u32 s21, s21, s23
	s_add_u32 s24, s24, s13
	s_addc_u32 s25, s25, s11
	s_cmpk_gt_i32 s42, 0x3fff
	s_waitcnt vmcnt(0)
	v_lshlrev_b32_e32 v160, 16, v77
	v_lshlrev_b32_e32 v129, 16, v75
	v_lshlrev_b32_e32 v128, 16, v74
	v_and_b32_e32 v163, 0xffff0000, v75
	v_and_b32_e32 v162, 0xffff0000, v74
	v_and_b32_e32 v161, 0xffff0000, v77
	v_lshlrev_b32_e32 v164, 16, v84
	v_and_b32_e32 v165, 0xffff0000, v84
	v_lshlrev_b32_e32 v131, 16, v89
	v_lshlrev_b32_e32 v130, 16, v88
	v_and_b32_e32 v167, 0xffff0000, v89
	v_and_b32_e32 v166, 0xffff0000, v88
	v_pk_add_f32 v[178:179], v[128:129], v[162:163]
	v_lshlrev_b32_e32 v133, 16, v91
	v_lshlrev_b32_e32 v108, 16, v96
	v_and_b32_e32 v109, 0xffff0000, v96
	v_lshlrev_b32_e32 v110, 16, v97
	v_and_b32_e32 v111, 0xffff0000, v97
	v_lshlrev_b32_e32 v168, 16, v98
	v_and_b32_e32 v169, 0xffff0000, v98
	v_lshlrev_b32_e32 v170, 16, v99
	v_and_b32_e32 v171, 0xffff0000, v99
	v_lshlrev_b32_e32 v132, 16, v90
	v_and_b32_e32 v173, 0xffff0000, v91
	v_and_b32_e32 v172, 0xffff0000, v90
	v_lshlrev_b32_e32 v96, 16, v142
	v_and_b32_e32 v97, 0xffff0000, v142
	v_lshlrev_b32_e32 v98, 16, v143
	v_and_b32_e32 v99, 0xffff0000, v143
	v_lshlrev_b32_e32 v142, 16, v112
	v_and_b32_e32 v143, 0xffff0000, v112
	v_lshlrev_b32_e32 v83, 16, v87
	v_lshlrev_b32_e32 v82, 16, v86
	v_and_b32_e32 v177, 0xffff0000, v87
	v_and_b32_e32 v176, 0xffff0000, v86
	v_lshlrev_b32_e32 v100, 16, v92
	v_and_b32_e32 v101, 0xffff0000, v92
	v_lshlrev_b32_e32 v104, 16, v93
	v_and_b32_e32 v105, 0xffff0000, v93
	v_lshlrev_b32_e32 v102, 16, v94
	v_and_b32_e32 v103, 0xffff0000, v94
	v_lshlrev_b32_e32 v106, 16, v95
	v_and_b32_e32 v107, 0xffff0000, v95
	v_lshlrev_b32_e32 v88, 16, v114
	v_and_b32_e32 v89, 0xffff0000, v114
	v_lshlrev_b32_e32 v92, 16, v115
	v_and_b32_e32 v93, 0xffff0000, v115
	v_lshlrev_b32_e32 v90, 16, v136
	v_and_b32_e32 v91, 0xffff0000, v136
	v_lshlrev_b32_e32 v94, 16, v137
	v_and_b32_e32 v95, 0xffff0000, v137
	v_pk_add_f32 v[160:161], v[160:161], -1.0 op_sel_hi:[1,0]
	v_pk_add_f32 v[136:137], v[164:165], -1.0 op_sel_hi:[1,0]
	v_pk_add_f32 v[164:165], v[130:131], v[166:167]
	v_pk_add_f32 v[114:115], v[168:169], -1.0 op_sel_hi:[1,0]
	v_pk_add_f32 v[168:169], v[132:133], v[172:173]
	v_pk_add_f32 v[86:87], v[142:143], -1.0 op_sel_hi:[1,0]
	v_pk_add_f32 v[142:143], v[82:83], v[176:177]
	v_add_f32_e32 v139, v178, v179
	v_pk_fma_f32 v[26:27], v[26:27], v[160:161], 1.0 op_sel_hi:[1,1,0]
	v_add_f32_e32 v160, v164, v165
	v_add_f32_e32 v161, v168, v169
	v_add_f32_e32 v164, v142, v143
	v_add_f32_dpp v139, v139, v139 quad_perm:[1,0,3,2] row_mask:0xf bank_mask:0xf bound_ctrl:1
	v_lshlrev_b32_e32 v158, 16, v76
	v_and_b32_e32 v159, 0xffff0000, v76
	v_lshlrev_b32_e32 v116, 16, v72
	v_and_b32_e32 v117, 0xffff0000, v72
	v_lshlrev_b32_e32 v120, 16, v73
	v_and_b32_e32 v121, 0xffff0000, v73
	v_lshlrev_b32_e32 v124, 16, v68
	v_and_b32_e32 v125, 0xffff0000, v68
	v_lshlrev_b32_e32 v126, 16, v69
	v_and_b32_e32 v127, 0xffff0000, v69
	v_lshlrev_b32_e32 v68, 16, v140
	v_and_b32_e32 v69, 0xffff0000, v140
	v_lshlrev_b32_e32 v72, 16, v141
	v_and_b32_e32 v73, 0xffff0000, v141
	v_lshlrev_b32_e32 v74, 16, v144
	v_and_b32_e32 v75, 0xffff0000, v144
	v_lshlrev_b32_e32 v76, 16, v145
	v_and_b32_e32 v77, 0xffff0000, v145
	v_lshlrev_b32_e32 v140, 16, v146
	v_and_b32_e32 v141, 0xffff0000, v146
	v_lshlrev_b32_e32 v144, 16, v147
	v_and_b32_e32 v145, 0xffff0000, v147
	v_lshlrev_b32_e32 v146, 16, v148
	v_and_b32_e32 v147, 0xffff0000, v148
	v_lshlrev_b32_e32 v148, 16, v149
	v_and_b32_e32 v149, 0xffff0000, v149
	v_add_f32_dpp v160, v160, v160 quad_perm:[1,0,3,2] row_mask:0xf bank_mask:0xf bound_ctrl:1
	v_add_f32_dpp v161, v161, v161 quad_perm:[1,0,3,2] row_mask:0xf bank_mask:0xf bound_ctrl:1
	v_add_f32_dpp v164, v164, v164 quad_perm:[1,0,3,2] row_mask:0xf bank_mask:0xf bound_ctrl:1
	v_add_f32_dpp v139, v139, v139 quad_perm:[2,3,0,1] row_mask:0xf bank_mask:0xf bound_ctrl:1
	v_lshlrev_b32_e32 v84, 16, v85
	v_and_b32_e32 v85, 0xffff0000, v85
	v_lshlrev_b32_e32 v174, 16, v113
	v_and_b32_e32 v175, 0xffff0000, v113
	v_xor_b32_e32 v183, 0x80000000, v149
	v_xor_b32_e32 v182, 0x80000000, v148
	v_xor_b32_e32 v185, 0x80000000, v147
	v_xor_b32_e32 v184, 0x80000000, v146
	v_add_f32_dpp v165, v160, v160 quad_perm:[2,3,0,1] row_mask:0xf bank_mask:0xf bound_ctrl:1
	v_add_f32_dpp v168, v161, v161 quad_perm:[2,3,0,1] row_mask:0xf bank_mask:0xf bound_ctrl:1
	v_add_f32_dpp v164, v164, v164 quad_perm:[2,3,0,1] row_mask:0xf bank_mask:0xf bound_ctrl:1
	v_lshlrev_b32_e32 v160, 16, v152
	v_and_b32_e32 v161, 0xffff0000, v152
	v_lshlrev_b32_e32 v152, 16, v153
	v_and_b32_e32 v153, 0xffff0000, v153
	v_add_f32_dpp v139, v139, v139 row_half_mirror row_mask:0xf bank_mask:0xf bound_ctrl:1
	v_lshlrev_b32_e32 v118, 16, v70
	v_and_b32_e32 v119, 0xffff0000, v70
	v_lshlrev_b32_e32 v122, 16, v71
	v_and_b32_e32 v123, 0xffff0000, v71
	v_lshlrev_b32_e32 v64, 16, v134
	v_and_b32_e32 v65, 0xffff0000, v134
	v_lshlrev_b32_e32 v70, 16, v135
	v_and_b32_e32 v71, 0xffff0000, v135
	v_pk_add_f32 v[158:159], v[158:159], -1.0 op_sel_hi:[1,0]
	v_pk_add_f32 v[134:135], v[84:85], -1.0 op_sel_hi:[1,0]
	v_pk_add_f32 v[112:113], v[170:171], -1.0 op_sel_hi:[1,0]
	v_pk_add_f32 v[84:85], v[174:175], -1.0 op_sel_hi:[1,0]
	v_lshlrev_b32_e32 v170, 16, v150
	v_and_b32_e32 v171, 0xffff0000, v150
	v_lshlrev_b32_e32 v150, 16, v151
	v_and_b32_e32 v151, 0xffff0000, v151
	v_xor_b32_e32 v175, 0x80000000, v141
	v_xor_b32_e32 v174, 0x80000000, v140
	v_xor_b32_e32 v181, 0x80000000, v145
	v_xor_b32_e32 v180, 0x80000000, v144
	v_add_f32_dpp v178, v165, v165 row_half_mirror row_mask:0xf bank_mask:0xf bound_ctrl:1
	v_add_f32_dpp v179, v168, v168 row_half_mirror row_mask:0xf bank_mask:0xf bound_ctrl:1
	v_add_f32_dpp v186, v164, v164 row_half_mirror row_mask:0xf bank_mask:0xf bound_ctrl:1
	v_lshlrev_b32_e32 v164, 16, v154
	v_and_b32_e32 v165, 0xffff0000, v154
	v_lshlrev_b32_e32 v154, 16, v155
	v_and_b32_e32 v155, 0xffff0000, v155
	v_pk_fma_f32 v[152:153], v[62:63], v[152:153], v[182:183] op_sel_hi:[0,1,1]
	v_pk_fma_f32 v[160:161], v[62:63], v[160:161], v[184:185] op_sel_hi:[0,1,1]
	v_add_f32_dpp v139, v139, v139 row_mirror row_mask:0xf bank_mask:0xf bound_ctrl:1
	v_pk_fma_f32 v[24:25], v[24:25], v[158:159], 1.0 op_sel_hi:[1,1,0]
	v_xor_b32_e32 v143, 0x80000000, v151
	v_xor_b32_e32 v142, 0x80000000, v150
	v_lshlrev_b32_e32 v168, 16, v156
	v_and_b32_e32 v169, 0xffff0000, v156
	v_lshlrev_b32_e32 v156, 16, v157
	v_and_b32_e32 v157, 0xffff0000, v157
	v_add_f32_dpp v178, v178, v178 row_mirror row_mask:0xf bank_mask:0xf bound_ctrl:1
	v_add_f32_dpp v179, v179, v179 row_mirror row_mask:0xf bank_mask:0xf bound_ctrl:1
	v_pk_fma_f32 v[164:165], v[62:63], v[164:165], v[174:175] op_sel_hi:[0,1,1]
	v_pk_fma_f32 v[154:155], v[62:63], v[154:155], v[180:181] op_sel_hi:[0,1,1]
	v_pk_fma_f32 v[12:13], v[12:13], v[160:161], v[146:147]
	v_pk_fma_f32 v[14:15], v[14:15], v[152:153], v[148:149]
	v_fmac_f32_e32 v162, 0xbc800000, v139
	v_fmac_f32_e32 v163, 0xbc800000, v139
	v_fmac_f32_e32 v129, 0xbc800000, v139
	v_xor_b32_e32 v159, 0x80000000, v171
	v_xor_b32_e32 v158, 0x80000000, v170
	v_pk_fma_f32 v[142:143], v[62:63], v[156:157], v[142:143] op_sel_hi:[0,1,1]
	v_fmac_f32_e32 v128, 0xbc800000, v139
	v_fmac_f32_e32 v166, 0xbc800000, v178
	v_fmac_f32_e32 v167, 0xbc800000, v178
	v_fmac_f32_e32 v131, 0xbc800000, v178
	v_fmac_f32_e32 v172, 0xbc800000, v179
	v_fmac_f32_e32 v173, 0xbc800000, v179
	v_fmac_f32_e32 v133, 0xbc800000, v179
	v_pk_fma_f32 v[10:11], v[10:11], v[154:155], v[144:145]
	v_pk_fma_f32 v[140:141], v[8:9], v[164:165], v[140:141]
	v_pk_mul_f32 v[14:15], v[14:15], v[26:27]
	v_pk_mul_f32 v[12:13], v[12:13], v[24:25]
	v_mov_b32_e32 v24, v129
	v_mov_b32_e32 v25, v163
	v_mov_b32_e32 v129, v162
	v_add_f32_dpp v182, v186, v186 row_mirror row_mask:0xf bank_mask:0xf bound_ctrl:1
	v_pk_fma_f32 v[146:147], v[62:63], v[168:169], v[158:159] op_sel_hi:[0,1,1]
	v_fmac_f32_e32 v130, 0xbc800000, v178
	v_fmac_f32_e32 v132, 0xbc800000, v179
	v_pk_fma_f32 v[18:19], v[18:19], v[142:143], v[150:151]
	v_mov_b32_e32 v26, v131
	v_mov_b32_e32 v27, v167
	v_mov_b32_e32 v131, v166
	v_mov_b32_e32 v142, v133
	v_mov_b32_e32 v143, v173
	v_mov_b32_e32 v133, v172
	v_pk_mul_f32 v[12:13], v[140:141], v[12:13]
	v_pk_mul_f32 v[10:11], v[10:11], v[14:15]
	v_pk_mul_f32 v[14:15], v[24:25], v[24:25]
	v_pk_mul_f32 v[140:141], v[128:129], v[128:129]
	v_fmac_f32_e32 v176, 0xbc800000, v182
	v_fmac_f32_e32 v177, 0xbc800000, v182
	v_fmac_f32_e32 v83, 0xbc800000, v182
	v_pk_fma_f32 v[16:17], v[16:17], v[146:147], v[170:171]
	v_pk_mul_f32 v[144:145], v[26:27], v[26:27]
	v_pk_mul_f32 v[146:147], v[130:131], v[130:131]
	v_pk_mul_f32 v[148:149], v[142:143], v[142:143]
	v_pk_mul_f32 v[150:151], v[132:133], v[132:133]
	v_pk_mul_f32 v[10:11], v[22:23], v[10:11]
	v_pk_mul_f32 v[12:13], v[20:21], v[12:13]
	v_pk_mov_b32 v[20:21], v[140:141], v[14:15] op_sel:[1,0]
	v_mov_b32_e32 v141, v15
	v_fmac_f32_e32 v82, 0xbc800000, v182
	v_mov_b32_e32 v8, v83
	v_mov_b32_e32 v9, v177
	v_mov_b32_e32 v83, v176
	v_pk_mov_b32 v[14:15], v[146:147], v[144:145] op_sel:[1,0]
	v_mov_b32_e32 v147, v145
	v_pk_mov_b32 v[22:23], v[150:151], v[148:149] op_sel:[1,0]
	v_mov_b32_e32 v151, v149
	v_pk_mov_b32 v[148:149], v[12:13], v[10:11] op_sel:[1,0]
	v_mov_b32_e32 v13, v11
	v_pk_add_f32 v[10:11], v[20:21], v[140:141]
	v_pk_mul_f32 v[152:153], v[8:9], v[8:9]
	v_pk_mul_f32 v[154:155], v[82:83], v[82:83]
	v_pk_add_f32 v[14:15], v[14:15], v[146:147]
	v_pk_add_f32 v[20:21], v[22:23], v[150:151]
	v_pk_add_f32 v[12:13], v[148:149], v[12:13]
	v_add_f32_e32 v10, v10, v11
	v_pk_mov_b32 v[144:145], v[154:155], v[152:153] op_sel:[1,0]
	v_mov_b32_e32 v155, v153
	v_add_f32_e32 v11, v14, v15
	v_add_f32_e32 v14, v20, v21
	v_add_f32_e32 v12, v12, v13
	v_add_f32_dpp v10, v10, v10 quad_perm:[1,0,3,2] row_mask:0xf bank_mask:0xf bound_ctrl:1
	v_pk_add_f32 v[22:23], v[144:145], v[154:155]
	v_add_f32_dpp v13, v14, v14 quad_perm:[1,0,3,2] row_mask:0xf bank_mask:0xf bound_ctrl:1
	v_add_f32_dpp v12, v12, v12 quad_perm:[1,0,3,2] row_mask:0xf bank_mask:0xf bound_ctrl:1
	v_add_f32_dpp v10, v10, v10 quad_perm:[2,3,0,1] row_mask:0xf bank_mask:0xf bound_ctrl:1
	v_add_f32_e32 v15, v22, v23
	v_add_f32_dpp v11, v11, v11 quad_perm:[1,0,3,2] row_mask:0xf bank_mask:0xf bound_ctrl:1
	v_add_f32_dpp v13, v13, v13 quad_perm:[2,3,0,1] row_mask:0xf bank_mask:0xf bound_ctrl:1
	v_add_f32_dpp v12, v12, v12 quad_perm:[2,3,0,1] row_mask:0xf bank_mask:0xf bound_ctrl:1
	v_add_f32_dpp v10, v10, v10 row_half_mirror row_mask:0xf bank_mask:0xf bound_ctrl:1
	v_add_f32_dpp v14, v15, v15 quad_perm:[1,0,3,2] row_mask:0xf bank_mask:0xf bound_ctrl:1
	v_add_f32_dpp v11, v11, v11 quad_perm:[2,3,0,1] row_mask:0xf bank_mask:0xf bound_ctrl:1
	v_add_f32_dpp v13, v13, v13 row_half_mirror row_mask:0xf bank_mask:0xf bound_ctrl:1
	v_add_f32_dpp v12, v12, v12 row_half_mirror row_mask:0xf bank_mask:0xf bound_ctrl:1
	v_add_f32_dpp v15, v10, v10 row_mirror row_mask:0xf bank_mask:0xf bound_ctrl:1
	v_add_f32_dpp v11, v11, v11 row_half_mirror row_mask:0xf bank_mask:0xf bound_ctrl:1
	v_add_f32_dpp v13, v13, v13 row_mirror row_mask:0xf bank_mask:0xf bound_ctrl:1
	v_add_f32_dpp v10, v12, v12 row_mirror row_mask:0xf bank_mask:0xf bound_ctrl:1
	v_fmamk_f32 v12, v15, 0x3c800000, v29
	v_add_f32_dpp v14, v14, v14 quad_perm:[2,3,0,1] row_mask:0xf bank_mask:0xf bound_ctrl:1
	v_add_f32_dpp v11, v11, v11 row_mirror row_mask:0xf bank_mask:0xf bound_ctrl:1
	v_fmamk_f32 v13, v13, 0x3c800000, v29
	v_mul_f32_e32 v15, 0x4f800000, v12
	v_cmp_gt_f32_e64 s[4:5], s29, v12
	v_add_f32_dpp v14, v14, v14 row_half_mirror row_mask:0xf bank_mask:0xf bound_ctrl:1
	v_fmamk_f32 v11, v11, 0x3c800000, v29
	v_mul_f32_e32 v21, 0x4f800000, v13
	v_cmp_gt_f32_e64 s[0:1], s29, v13
	v_cndmask_b32_e64 v12, v12, v15, s[4:5]
	v_add_f32_dpp v14, v14, v14 row_mirror row_mask:0xf bank_mask:0xf bound_ctrl:1
	v_cndmask_b32_e64 v13, v13, v21, s[0:1]
	v_sqrt_f32_e32 v15, v12
	v_fmamk_f32 v14, v14, 0x3c800000, v29
	v_sqrt_f32_e32 v21, v13
	v_mul_f32_e32 v22, 0x4f800000, v14
	v_cmp_gt_f32_e64 s[2:3], s29, v14
	v_add_u32_e32 v23, -1, v15
	s_nop 0
	v_cndmask_b32_e64 v14, v14, v22, s[2:3]
	v_sqrt_f32_e32 v22, v14
	v_add_u32_e32 v139, 1, v15
	v_add_u32_e32 v144, -1, v21
	v_fma_f32 v148, -v23, v15, v12
	v_add_u32_e32 v145, 1, v21
	v_fma_f32 v149, -v139, v15, v12
	v_fma_f32 v152, -v144, v21, v13
	v_cmp_ge_f32_e64 s[6:7], 0, v148
	v_fma_f32 v153, -v145, v21, v13
	s_nop 0
	v_cndmask_b32_e64 v15, v15, v23, s[6:7]
	v_cmp_ge_f32_e64 s[8:9], 0, v152
	v_cmp_lt_f32_e64 s[16:17], 0, v149
	v_add_u32_e32 v146, -1, v22
	v_cndmask_b32_e64 v21, v21, v144, s[8:9]
	v_cmp_lt_f32_e64 s[8:9], 0, v153
	v_cndmask_b32_e64 v15, v15, v139, s[16:17]
	v_add_u32_e32 v147, 1, v22
	v_fma_f32 v154, -v146, v22, v14
	v_cndmask_b32_e64 v21, v21, v145, s[8:9]
	v_mul_f32_e32 v23, 0x37800000, v15
	v_fma_f32 v155, -v147, v22, v14
	v_cmp_ge_f32_e64 s[14:15], 0, v154
	v_mul_f32_e32 v140, 0x37800000, v21
	v_cndmask_b32_e64 v15, v15, v23, s[4:5]
	v_cmp_class_f32_e64 s[4:5], v12, v138
	v_cndmask_b32_e64 v22, v22, v146, s[14:15]
	v_cmp_lt_f32_e64 s[14:15], 0, v155
	v_cndmask_b32_e64 v21, v21, v140, s[0:1]
	v_cmp_class_f32_e64 s[0:1], v13, v138
	v_cndmask_b32_e64 v12, v15, v12, s[4:5]
	v_cndmask_b32_e64 v22, v22, v147, s[14:15]
	v_cndmask_b32_e64 v21, v21, v13, s[0:1]
	v_mul_f32_e32 v141, 0x37800000, v22
	v_sqrt_f32_e32 v11, v11
	v_cndmask_b32_e64 v22, v22, v141, s[2:3]
	v_cmp_class_f32_e64 s[2:3], v14, v138
	v_div_scale_f32 v15, s[0:1], v11, v11, 1.0
	s_nop 0
	v_cndmask_b32_e64 v139, v22, v14, s[2:3]
	v_div_scale_f32 v22, s[2:3], v21, v21, 1.0
	v_rcp_f32_e32 v141, v15
	v_rcp_f32_e32 v144, v22
	v_fma_f32 v146, -v15, v141, 1.0
	v_div_scale_f32 v20, s[0:1], 1.0, v11, 1.0
	v_fma_f32 v147, -v22, v144, 1.0
	v_fmac_f32_e32 v141, v146, v141
	v_div_scale_f32 v23, s[4:5], 1.0, v21, 1.0
	v_fmac_f32_e32 v144, v147, v144
	v_mul_f32_e32 v146, v20, v141
	v_mul_f32_e32 v147, v23, v144
	v_fma_f32 v149, -v15, v146, v20
	v_fma_f32 v150, -v22, v147, v23
	v_fmac_f32_e32 v146, v149, v141
	v_fmac_f32_e32 v147, v150, v144
	v_fma_f32 v14, -v15, v146, v20
	v_rcp_f32_e32 v12, v12
	s_mov_b64 vcc, s[0:1]
	v_fma_f32 v22, -v22, v147, v23
	v_div_fmas_f32 v20, v14, v141, v146
	v_pk_mul_f32 v[14:15], v[24:25], v[12:13] op_sel_hi:[1,0]
	v_pk_mul_f32 v[12:13], v[128:129], v[12:13] op_sel_hi:[1,0]
	s_mov_b64 vcc, s[4:5]
	v_div_fixup_f32 v20, v20, v11, 1.0
	v_div_fmas_f32 v11, v22, v144, v147
	v_pk_fma_f32 v[0:1], v[0:1], v[12:13], v[4:5]
	v_pk_fma_f32 v[2:3], v[2:3], v[14:15], v[6:7]
	v_pk_fma_f32 v[0:1], v[16:17], v[10:11], v[0:1] op_sel_hi:[1,0,1]
	v_pk_fma_f32 v[2:3], v[18:19], v[10:11], v[2:3] op_sel_hi:[1,0,1]
	v_pk_mul_f32 v[0:1], v[0:1], v[116:117]
	v_pk_mul_f32 v[2:3], v[2:3], v[120:121]
	v_pk_fma_f32 v[0:1], v[0:1], v[118:119], v[124:125]
	v_pk_fma_f32 v[2:3], v[2:3], v[122:123], v[126:127]
	v_cvt_pk_bf16_f32 v0, v0, v1
	v_cvt_pk_bf16_f32 v1, v2, v3
	v_div_fixup_f32 v4, v11, v21, 1.0
	global_store_dwordx2 v[58:59], v[0:1], off
	v_pk_mul_f32 v[26:27], v[26:27], v[20:21] op_sel_hi:[1,0]
	v_pk_mul_f32 v[128:129], v[130:131], v[20:21] op_sel_hi:[1,0]
	v_pk_mul_f32 v[130:131], v[142:143], v[4:5] op_sel_hi:[1,0]
	v_pk_mul_f32 v[132:133], v[132:133], v[4:5] op_sel_hi:[1,0]
	global_load_dwordx2 v[120:121], v[60:61], off offset:512
	global_load_dwordx2 v[122:123], v[60:61], off offset:2560
	global_load_dwordx2 v[124:125], v[66:67], off offset:512
	global_load_dwordx2 v[126:127], v[78:79], off offset:512
	global_load_dwordx2 v[140:141], v[78:79], off offset:2560
	global_load_dwordx2 v[142:143], v[80:81], off offset:512
	global_load_dwordx4 v[0:3], v[36:37], off offset:1024
	global_load_dwordx4 v[4:7], v[40:41], off offset:1024
	global_load_dwordx4 v[10:13], v[42:43], off offset:1024
	global_load_dwordx4 v[14:17], v[30:31], off offset:1024
	global_load_dwordx4 v[18:21], v[44:45], off
	global_load_dwordx4 v[22:25], v[46:47], off
	global_load_dwordx4 v[116:119], v[38:39], off offset:1024
	v_div_scale_f32 v156, s[2:3], v139, v139, 1.0
	s_nop 0
	v_rcp_f32_e32 v158, v156
	v_div_scale_f32 v157, s[2:3], 1.0, v139, 1.0
	s_mov_b64 vcc, s[2:3]
	v_fma_f32 v159, -v156, v158, 1.0
	v_fmac_f32_e32 v158, v159, v158
	s_waitcnt vmcnt(12)
	v_lshlrev_b32_e32 v144, 16, v120
	v_and_b32_e32 v145, 0xffff0000, v120
	v_lshlrev_b32_e32 v120, 16, v121
	v_and_b32_e32 v121, 0xffff0000, v121
	s_waitcnt vmcnt(11)
	v_lshlrev_b32_e32 v146, 16, v122
	v_and_b32_e32 v147, 0xffff0000, v122
	v_lshlrev_b32_e32 v122, 16, v123
	v_and_b32_e32 v123, 0xffff0000, v123
	s_waitcnt vmcnt(9)
	v_lshlrev_b32_e32 v150, 16, v126
	v_and_b32_e32 v151, 0xffff0000, v126
	v_lshlrev_b32_e32 v126, 16, v127
	v_and_b32_e32 v127, 0xffff0000, v127
	s_waitcnt vmcnt(8)
	v_lshlrev_b32_e32 v152, 16, v140
	v_and_b32_e32 v153, 0xffff0000, v140
	v_lshlrev_b32_e32 v140, 16, v141
	v_and_b32_e32 v141, 0xffff0000, v141
	s_waitcnt vmcnt(4)
	v_pk_fma_f32 v[4:5], v[4:5], v[128:129], v[10:11]
	v_pk_fma_f32 v[6:7], v[6:7], v[26:27], v[12:13]
	v_xor_b32_e32 v11, 0x80000000, v145
	v_xor_b32_e32 v10, 0x80000000, v144
	v_xor_b32_e32 v13, 0x80000000, v121
	v_xor_b32_e32 v12, 0x80000000, v120
	v_xor_b32_e32 v27, 0x80000000, v123
	v_xor_b32_e32 v26, 0x80000000, v122
	v_xor_b32_e32 v129, 0x80000000, v147
	v_xor_b32_e32 v128, 0x80000000, v146
	v_pk_fma_f32 v[10:11], v[62:63], v[150:151], v[10:11] op_sel_hi:[0,1,1]
	v_pk_fma_f32 v[12:13], v[62:63], v[126:127], v[12:13] op_sel_hi:[0,1,1]
	v_pk_fma_f32 v[26:27], v[62:63], v[140:141], v[26:27] op_sel_hi:[0,1,1]
	v_pk_fma_f32 v[126:127], v[62:63], v[152:153], v[128:129] op_sel_hi:[0,1,1]
	v_pk_fma_f32 v[0:1], v[0:1], v[136:137], 1.0 op_sel_hi:[1,1,0]
	v_pk_fma_f32 v[2:3], v[2:3], v[134:135], 1.0 op_sel_hi:[1,1,0]
	s_waitcnt vmcnt(3)
	v_pk_fma_f32 v[12:13], v[16:17], v[12:13], v[120:121]
	v_pk_fma_f32 v[10:11], v[14:15], v[10:11], v[144:145]
	s_waitcnt vmcnt(2)
	v_pk_fma_f32 v[14:15], v[18:19], v[126:127], v[146:147]
	v_pk_fma_f32 v[16:17], v[20:21], v[26:27], v[122:123]
	v_pk_mul_f32 v[0:1], v[14:15], v[0:1]
	v_pk_mul_f32 v[2:3], v[16:17], v[2:3]
	v_pk_mul_f32 v[0:1], v[10:11], v[0:1]
	v_pk_mul_f32 v[2:3], v[12:13], v[2:3]
	s_waitcnt vmcnt(0)
	v_pk_mul_f32 v[0:1], v[116:117], v[0:1]
	v_pk_mul_f32 v[2:3], v[118:119], v[2:3]
	v_lshlrev_b32_e32 v148, 16, v124
	v_pk_mov_b32 v[10:11], v[0:1], v[2:3] op_sel:[1,0]
	v_mov_b32_e32 v1, v3
	v_pk_add_f32 v[0:1], v[10:11], v[0:1]
	v_and_b32_e32 v149, 0xffff0000, v124
	v_add_f32_e32 v0, v0, v1
	v_lshlrev_b32_e32 v124, 16, v125
	v_and_b32_e32 v125, 0xffff0000, v125
	v_add_f32_dpp v0, v0, v0 quad_perm:[1,0,3,2] row_mask:0xf bank_mask:0xf bound_ctrl:1
	v_lshlrev_b32_e32 v154, 16, v142
	v_and_b32_e32 v155, 0xffff0000, v142
	v_lshlrev_b32_e32 v142, 16, v143
	v_and_b32_e32 v143, 0xffff0000, v143
	v_xor_b32_e32 v135, 0x80000000, v125
	v_xor_b32_e32 v134, 0x80000000, v124
	v_xor_b32_e32 v137, 0x80000000, v149
	v_xor_b32_e32 v136, 0x80000000, v148
	v_add_f32_dpp v0, v0, v0 quad_perm:[2,3,0,1] row_mask:0xf bank_mask:0xf bound_ctrl:1
	v_pk_fma_f32 v[128:129], v[62:63], v[142:143], v[134:135] op_sel_hi:[0,1,1]
	v_pk_fma_f32 v[134:135], v[62:63], v[154:155], v[136:137] op_sel_hi:[0,1,1]
	v_add_f32_dpp v0, v0, v0 row_half_mirror row_mask:0xf bank_mask:0xf bound_ctrl:1
	v_pk_fma_f32 v[18:19], v[22:23], v[134:135], v[148:149]
	v_pk_fma_f32 v[20:21], v[24:25], v[128:129], v[124:125]
	v_add_f32_dpp v0, v0, v0 row_mirror row_mask:0xf bank_mask:0xf bound_ctrl:1
	v_pk_fma_f32 v[2:3], v[20:21], v[0:1], v[6:7] op_sel_hi:[1,0,1]
	v_pk_fma_f32 v[0:1], v[18:19], v[0:1], v[4:5] op_sel_hi:[1,0,1]
	v_pk_mul_f32 v[2:3], v[2:3], v[104:105]
	v_pk_mul_f32 v[0:1], v[0:1], v[100:101]
	v_pk_fma_f32 v[2:3], v[2:3], v[106:107], v[110:111]
	v_pk_fma_f32 v[0:1], v[0:1], v[102:103], v[108:109]
	s_nop 0
	v_cvt_pk_bf16_f32 v0, v0, v1
	v_cvt_pk_bf16_f32 v1, v2, v3
	global_store_dwordx2 v[58:59], v[0:1], off offset:512
	global_load_dwordx2 v[26:27], v[60:61], off offset:1024
	global_load_dwordx2 v[104:105], v[60:61], off offset:3072
	global_load_dwordx2 v[106:107], v[66:67], off offset:1024
	global_load_dwordx2 v[108:109], v[78:79], off offset:1024
	global_load_dwordx2 v[110:111], v[78:79], off offset:3072
	global_load_dwordx2 v[116:117], v[80:81], off offset:1024
	global_load_dwordx4 v[0:3], v[36:37], off offset:2048
	global_load_dwordx4 v[4:7], v[40:41], off offset:2048
	global_load_dwordx4 v[10:13], v[42:43], off offset:2048
	global_load_dwordx4 v[14:17], v[30:31], off offset:2048
	global_load_dwordx4 v[18:21], v[48:49], off
	global_load_dwordx4 v[22:25], v[50:51], off
	global_load_dwordx4 v[100:103], v[38:39], off offset:2048
	s_waitcnt vmcnt(12)
	v_lshlrev_b32_e32 v118, 16, v26
	v_and_b32_e32 v119, 0xffff0000, v26
	v_lshlrev_b32_e32 v26, 16, v27
	v_and_b32_e32 v27, 0xffff0000, v27
	s_waitcnt vmcnt(11)
	v_lshlrev_b32_e32 v120, 16, v104
	v_and_b32_e32 v121, 0xffff0000, v104
	v_lshlrev_b32_e32 v104, 16, v105
	v_and_b32_e32 v105, 0xffff0000, v105
	s_waitcnt vmcnt(9)
	v_lshlrev_b32_e32 v124, 16, v108
	v_and_b32_e32 v125, 0xffff0000, v108
	v_lshlrev_b32_e32 v108, 16, v109
	v_and_b32_e32 v109, 0xffff0000, v109
	s_waitcnt vmcnt(8)
	v_lshlrev_b32_e32 v126, 16, v110
	v_and_b32_e32 v127, 0xffff0000, v110
	v_lshlrev_b32_e32 v110, 16, v111
	v_and_b32_e32 v111, 0xffff0000, v111
	s_waitcnt vmcnt(6)
	v_pk_fma_f32 v[0:1], v[0:1], v[114:115], 1.0 op_sel_hi:[1,1,0]
	v_pk_fma_f32 v[2:3], v[2:3], v[112:113], 1.0 op_sel_hi:[1,1,0]
	s_waitcnt vmcnt(4)
	v_pk_fma_f32 v[4:5], v[4:5], v[132:133], v[10:11]
	v_pk_fma_f32 v[6:7], v[6:7], v[130:131], v[12:13]
	v_xor_b32_e32 v11, 0x80000000, v119
	v_xor_b32_e32 v10, 0x80000000, v118
	v_xor_b32_e32 v13, 0x80000000, v27
	v_xor_b32_e32 v12, 0x80000000, v26
	v_xor_b32_e32 v113, 0x80000000, v105
	v_xor_b32_e32 v112, 0x80000000, v104
	v_xor_b32_e32 v115, 0x80000000, v121
	v_xor_b32_e32 v114, 0x80000000, v120
	v_pk_fma_f32 v[10:11], v[62:63], v[124:125], v[10:11] op_sel_hi:[0,1,1]
	v_pk_fma_f32 v[12:13], v[62:63], v[108:109], v[12:13] op_sel_hi:[0,1,1]
	v_pk_fma_f32 v[108:109], v[62:63], v[110:111], v[112:113] op_sel_hi:[0,1,1]
	v_pk_fma_f32 v[110:111], v[62:63], v[126:127], v[114:115] op_sel_hi:[0,1,1]
	s_waitcnt vmcnt(3)
	v_pk_fma_f32 v[12:13], v[16:17], v[12:13], v[26:27]
	v_pk_fma_f32 v[10:11], v[14:15], v[10:11], v[118:119]
	s_waitcnt vmcnt(2)
	v_pk_fma_f32 v[14:15], v[18:19], v[110:111], v[120:121]
	v_pk_fma_f32 v[16:17], v[20:21], v[108:109], v[104:105]
	v_pk_mul_f32 v[0:1], v[14:15], v[0:1]
	v_pk_mul_f32 v[2:3], v[16:17], v[2:3]
	v_pk_mul_f32 v[0:1], v[10:11], v[0:1]
	v_pk_mul_f32 v[2:3], v[12:13], v[2:3]
	s_waitcnt vmcnt(0)
	v_pk_mul_f32 v[0:1], v[100:101], v[0:1]
	v_pk_mul_f32 v[2:3], v[102:103], v[2:3]
	v_lshlrev_b32_e32 v122, 16, v106
	v_pk_mov_b32 v[10:11], v[0:1], v[2:3] op_sel:[1,0]
	v_mov_b32_e32 v1, v3
	v_pk_add_f32 v[0:1], v[10:11], v[0:1]
	v_and_b32_e32 v123, 0xffff0000, v106
	v_add_f32_e32 v0, v0, v1
	v_lshlrev_b32_e32 v106, 16, v107
	v_and_b32_e32 v107, 0xffff0000, v107
	v_add_f32_dpp v0, v0, v0 quad_perm:[1,0,3,2] row_mask:0xf bank_mask:0xf bound_ctrl:1
	v_lshlrev_b32_e32 v128, 16, v116
	v_and_b32_e32 v129, 0xffff0000, v116
	v_lshlrev_b32_e32 v116, 16, v117
	v_and_b32_e32 v117, 0xffff0000, v117
	v_xor_b32_e32 v131, 0x80000000, v107
	v_xor_b32_e32 v130, 0x80000000, v106
	v_xor_b32_e32 v133, 0x80000000, v123
	v_xor_b32_e32 v132, 0x80000000, v122
	v_add_f32_dpp v0, v0, v0 quad_perm:[2,3,0,1] row_mask:0xf bank_mask:0xf bound_ctrl:1
	v_pk_fma_f32 v[112:113], v[62:63], v[116:117], v[130:131] op_sel_hi:[0,1,1]
	v_pk_fma_f32 v[114:115], v[62:63], v[128:129], v[132:133] op_sel_hi:[0,1,1]
	v_add_f32_dpp v0, v0, v0 row_half_mirror row_mask:0xf bank_mask:0xf bound_ctrl:1
	v_pk_fma_f32 v[18:19], v[22:23], v[114:115], v[122:123]
	v_pk_fma_f32 v[20:21], v[24:25], v[112:113], v[106:107]
	v_add_f32_dpp v0, v0, v0 row_mirror row_mask:0xf bank_mask:0xf bound_ctrl:1
	v_pk_fma_f32 v[2:3], v[20:21], v[0:1], v[6:7] op_sel_hi:[1,0,1]
	v_pk_fma_f32 v[0:1], v[18:19], v[0:1], v[4:5] op_sel_hi:[1,0,1]
	v_pk_mul_f32 v[2:3], v[2:3], v[92:93]
	v_pk_mul_f32 v[0:1], v[0:1], v[88:89]
	v_pk_fma_f32 v[2:3], v[2:3], v[94:95], v[98:99]
	v_pk_fma_f32 v[0:1], v[0:1], v[90:91], v[96:97]
	v_mul_f32_e32 v94, v157, v158
	v_cvt_pk_bf16_f32 v0, v0, v1
	v_cvt_pk_bf16_f32 v1, v2, v3
	global_store_dwordx2 v[58:59], v[0:1], off offset:1024
	global_load_dwordx2 v[26:27], v[60:61], off offset:1536
	s_nop 0
	global_load_dwordx2 v[60:61], v[60:61], off offset:3584
	s_nop 0
	global_load_dwordx2 v[66:67], v[66:67], off offset:1536
	s_nop 0
	global_load_dwordx2 v[88:89], v[78:79], off offset:1536
	global_load_dwordx2 v[90:91], v[78:79], off offset:3584
	global_load_dwordx2 v[92:93], v[80:81], off offset:1536
	global_load_dwordx4 v[0:3], v[36:37], off offset:3072
	global_load_dwordx4 v[4:7], v[40:41], off offset:3072
	global_load_dwordx4 v[10:13], v[42:43], off offset:3072
	global_load_dwordx4 v[14:17], v[30:31], off offset:3072
	global_load_dwordx4 v[18:21], v[52:53], off
	global_load_dwordx4 v[22:25], v[38:39], off offset:3072
	global_load_dwordx4 v[78:81], v[54:55], off
	v_fma_f32 v95, -v156, v94, v157
	v_fmac_f32_e32 v94, v95, v158
	v_fma_f32 v95, -v156, v94, v157
	v_div_fmas_f32 v94, v95, v158, v94
	v_div_fixup_f32 v94, v94, v139, 1.0
	v_pk_mul_f32 v[8:9], v[8:9], v[94:95] op_sel_hi:[1,0]
	v_pk_mul_f32 v[82:83], v[82:83], v[94:95] op_sel_hi:[1,0]
	s_waitcnt vmcnt(12)
; template <int ph>
; __device__ __forceinline__ void run_phase(const Args& args, LAS unsigned char* lds, const int G, const int bx, const bool fin = true) {
;     ...
;         for (int row = gw; row < MP; row += ngw) {
	v_lshlrev_b32_e32 v94, 16, v26
	v_and_b32_e32 v95, 0xffff0000, v26
	s_waitcnt vmcnt(11)
	v_lshlrev_b32_e32 v96, 16, v60
	v_and_b32_e32 v97, 0xffff0000, v60
	v_lshlrev_b32_e32 v60, 16, v61
	v_and_b32_e32 v61, 0xffff0000, v61
	v_lshlrev_b32_e32 v26, 16, v27
	v_and_b32_e32 v27, 0xffff0000, v27
	s_waitcnt vmcnt(9)
	v_lshlrev_b32_e32 v100, 16, v88
	v_and_b32_e32 v101, 0xffff0000, v88
	s_waitcnt vmcnt(8)
	v_lshlrev_b32_e32 v102, 16, v90
	v_and_b32_e32 v103, 0xffff0000, v90
	v_lshlrev_b32_e32 v90, 16, v91
	v_and_b32_e32 v91, 0xffff0000, v91
	s_waitcnt vmcnt(4)
	v_pk_fma_f32 v[4:5], v[4:5], v[82:83], v[10:11]
	v_pk_fma_f32 v[6:7], v[6:7], v[8:9], v[12:13]
	v_xor_b32_e32 v9, 0x80000000, v95
	v_xor_b32_e32 v8, 0x80000000, v94
	v_xor_b32_e32 v13, 0x80000000, v61
	v_xor_b32_e32 v12, 0x80000000, v60
	v_xor_b32_e32 v83, 0x80000000, v97
	v_xor_b32_e32 v82, 0x80000000, v96
	v_lshlrev_b32_e32 v88, 16, v89
	v_and_b32_e32 v89, 0xffff0000, v89
	v_xor_b32_e32 v11, 0x80000000, v27
	v_xor_b32_e32 v10, 0x80000000, v26
	v_pk_fma_f32 v[8:9], v[62:63], v[100:101], v[8:9] op_sel_hi:[0,1,1]
	v_pk_fma_f32 v[12:13], v[62:63], v[90:91], v[12:13] op_sel_hi:[0,1,1]
	v_pk_fma_f32 v[82:83], v[62:63], v[102:103], v[82:83] op_sel_hi:[0,1,1]
	v_pk_fma_f32 v[0:1], v[0:1], v[86:87], 1.0 op_sel_hi:[1,1,0]
	v_pk_fma_f32 v[2:3], v[2:3], v[84:85], 1.0 op_sel_hi:[1,1,0]
	v_pk_fma_f32 v[10:11], v[62:63], v[88:89], v[10:11] op_sel_hi:[0,1,1]
	s_waitcnt vmcnt(3)
	v_pk_fma_f32 v[8:9], v[14:15], v[8:9], v[94:95]
	s_waitcnt vmcnt(2)
	v_pk_fma_f32 v[14:15], v[18:19], v[82:83], v[96:97]
	v_pk_fma_f32 v[12:13], v[20:21], v[12:13], v[60:61]
	v_pk_fma_f32 v[10:11], v[16:17], v[10:11], v[26:27]
	v_pk_mul_f32 v[2:3], v[12:13], v[2:3]
	v_pk_mul_f32 v[0:1], v[14:15], v[0:1]
	v_pk_mul_f32 v[2:3], v[10:11], v[2:3]
	v_pk_mul_f32 v[0:1], v[8:9], v[0:1]
	s_waitcnt vmcnt(1)
	v_pk_mul_f32 v[2:3], v[24:25], v[2:3]
	v_pk_mul_f32 v[0:1], v[22:23], v[0:1]
	v_lshlrev_b32_e32 v98, 16, v66
	v_pk_mov_b32 v[8:9], v[0:1], v[2:3] op_sel:[1,0]
	v_mov_b32_e32 v1, v3
	v_pk_add_f32 v[0:1], v[8:9], v[0:1]
	v_and_b32_e32 v99, 0xffff0000, v66
	v_add_f32_e32 v0, v0, v1
	v_lshlrev_b32_e32 v66, 16, v67
	v_and_b32_e32 v67, 0xffff0000, v67
	v_add_f32_dpp v0, v0, v0 quad_perm:[1,0,3,2] row_mask:0xf bank_mask:0xf bound_ctrl:1
	v_lshlrev_b32_e32 v104, 16, v92
	v_and_b32_e32 v105, 0xffff0000, v92
	v_lshlrev_b32_e32 v92, 16, v93
	v_and_b32_e32 v93, 0xffff0000, v93
	v_xor_b32_e32 v85, 0x80000000, v67
	v_xor_b32_e32 v84, 0x80000000, v66
	v_xor_b32_e32 v87, 0x80000000, v99
	v_xor_b32_e32 v86, 0x80000000, v98
	v_add_f32_dpp v0, v0, v0 quad_perm:[2,3,0,1] row_mask:0xf bank_mask:0xf bound_ctrl:1
	v_pk_fma_f32 v[84:85], v[62:63], v[92:93], v[84:85] op_sel_hi:[0,1,1]
	v_pk_fma_f32 v[86:87], v[62:63], v[104:105], v[86:87] op_sel_hi:[0,1,1]
	v_add_f32_dpp v0, v0, v0 row_half_mirror row_mask:0xf bank_mask:0xf bound_ctrl:1
	s_waitcnt vmcnt(0)
	v_pk_fma_f32 v[16:17], v[78:79], v[86:87], v[98:99]
	v_pk_fma_f32 v[18:19], v[80:81], v[84:85], v[66:67]
	v_add_f32_dpp v0, v0, v0 row_mirror row_mask:0xf bank_mask:0xf bound_ctrl:1
	v_pk_fma_f32 v[2:3], v[18:19], v[0:1], v[6:7] op_sel_hi:[1,0,1]
	v_pk_fma_f32 v[0:1], v[16:17], v[0:1], v[4:5] op_sel_hi:[1,0,1]
	v_pk_mul_f32 v[2:3], v[2:3], v[70:71]
	v_pk_mul_f32 v[0:1], v[0:1], v[64:65]
	v_pk_fma_f32 v[2:3], v[2:3], v[72:73], v[76:77]
	v_pk_fma_f32 v[0:1], v[0:1], v[68:69], v[74:75]
	s_nop 0
	v_cvt_pk_bf16_f32 v0, v0, v1
	v_cvt_pk_bf16_f32 v1, v2, v3
	global_store_dwordx2 v[58:59], v[0:1], off offset:1536
	s_cbranch_scc0 .LBB0_1140

; template <int ph>
; __device__ __forceinline__ void run_phase(const Args& args, LAS unsigned char* lds, const int G, const int bx, const bool fin = true) {
;     ...
;         for (int row = MP + gw; row < MT; row += ngw) {
;             const int si = row - MP;
;             POST_ROW(const float* sb = state_shift + (size_t)si * RP + c; qr = *(const f32x4*)(sb); qk = *(const f32x4*)(sb + 1024); qv = *(const f32x4*)(sb + 2048);)
.LBB0_1143:
	v_mad_i64_i32 v[58:59], s[0:1], s10, v138, v[56:57]
	v_lshl_add_u64 v[62:63], s[16:17], 0, v[28:29]
	v_add_co_u32_e64 v66, s[0:1], s26, v62
	v_lshl_add_u64 v[60:61], s[22:23], 0, v[28:29]
	s_nop 0
	v_addc_co_u32_e64 v67, s[0:1], 0, v63, s[0:1]
	v_add_co_u32_e64 v68, s[0:1], s27, v62
	v_add_co_u32_e32 v64, vcc, 0x9e00000, v60
	s_nop 0
	v_addc_co_u32_e64 v69, s[0:1], 0, v63, s[0:1]
	v_add_co_u32_e64 v70, s[0:1], s29, v62
	v_addc_co_u32_e32 v65, vcc, 0, v61, vcc
	s_nop 0
	v_addc_co_u32_e64 v71, s[0:1], 0, v63, s[0:1]
	v_add_co_u32_e64 v72, s[0:1], s36, v62
	v_add_co_u32_e32 v60, vcc, s19, v60
	s_nop 0
	v_addc_co_u32_e64 v73, s[0:1], 0, v63, s[0:1]
	v_add_co_u32_e64 v74, s[0:1], s37, v62
	v_addc_co_u32_e32 v61, vcc, 0, v61, vcc
	global_load_dwordx4 v[12:15], v[30:31], off
	global_load_dwordx4 v[8:11], v[32:33], off
	global_load_dwordx4 v[16:19], v[34:35], off
	global_load_dwordx4 v[24:27], v[36:37], off
	global_load_dwordx4 v[20:23], v[38:39], off
	global_load_dwordx4 v[0:3], v[40:41], off
	global_load_dwordx4 v[4:7], v[42:43], off
	global_load_dwordx4 v[142:145], v[58:59], off
	v_addc_co_u32_e64 v75, s[0:1], 0, v63, s[0:1]
	global_load_dwordx2 v[76:77], v[66:67], off
	global_load_dwordx2 v[78:79], v[68:69], off
	global_load_dwordx2 v[80:81], v[70:71], off
	global_load_dwordx2 v[82:83], v[72:73], off
	global_load_dwordx2 v[84:85], v[74:75], off
	global_load_dwordx2 v[86:87], v[66:67], off offset:512
	global_load_dwordx2 v[88:89], v[68:69], off offset:512
	global_load_dwordx2 v[90:91], v[70:71], off offset:512
	global_load_dwordx2 v[92:93], v[72:73], off offset:512
	global_load_dwordx2 v[94:95], v[74:75], off offset:512
	global_load_dwordx2 v[96:97], v[66:67], off offset:1024
	global_load_dwordx2 v[98:99], v[68:69], off offset:1024
	global_load_dwordx2 v[112:113], v[70:71], off offset:1024
	global_load_dwordx2 v[114:115], v[72:73], off offset:1024
	global_load_dwordx2 v[134:135], v[66:67], off offset:1536
	global_load_dwordx2 v[136:137], v[68:69], off offset:1536
	global_load_dwordx2 v[154:155], v[70:71], off offset:1536
	global_load_dwordx2 v[156:157], v[72:73], off offset:1536
	global_load_dwordx2 v[158:159], v[74:75], off offset:1024
	global_load_dwordx2 v[160:161], v[74:75], off offset:1536
	v_add_co_u32_e32 v66, vcc, s24, v58
	global_load_dwordx2 v[162:163], v[64:65], off
	global_load_dwordx2 v[164:165], v[64:65], off offset:2048
	global_load_dwordx2 v[166:167], v[60:61], off
	v_addc_co_u32_e32 v67, vcc, 0, v59, vcc
	v_add_co_u32_e32 v68, vcc, s25, v58
	v_add_co_u32_e64 v62, s[0:1], s38, v62
	s_nop 0
	v_addc_co_u32_e32 v69, vcc, 0, v59, vcc
	global_load_dwordx4 v[146:149], v[68:69], off offset:-4096
	global_load_dwordx4 v[150:153], v[68:69], off
	s_add_i32 s10, s10, s18
	v_addc_co_u32_e64 v63, s[0:1], 0, v63, s[0:1]
	s_add_i32 s0, s10, 0x4000
	s_add_u32 s16, s16, s20
	s_addc_u32 s17, s17, s21
	s_add_u32 s22, s22, s13
	s_addc_u32 s23, s23, s11
	s_cmpk_lt_i32 s0, 0x4080
	s_waitcnt vmcnt(0)
	v_lshlrev_b32_e32 v170, 16, v77
	v_and_b32_e32 v171, 0xffff0000, v77
	v_lshlrev_b32_e32 v129, 16, v79
	v_lshlrev_b32_e32 v128, 16, v78
	v_and_b32_e32 v173, 0xffff0000, v79
	v_and_b32_e32 v172, 0xffff0000, v78
	v_lshlrev_b32_e32 v168, 16, v76
	v_and_b32_e32 v169, 0xffff0000, v76
	v_lshlrev_b32_e32 v116, 16, v80
	v_and_b32_e32 v117, 0xffff0000, v80
	v_lshlrev_b32_e32 v120, 16, v81
	v_and_b32_e32 v121, 0xffff0000, v81
	v_lshlrev_b32_e32 v118, 16, v82
	v_and_b32_e32 v119, 0xffff0000, v82
	v_lshlrev_b32_e32 v122, 16, v83
	v_and_b32_e32 v123, 0xffff0000, v83
	v_lshlrev_b32_e32 v124, 16, v84
	v_and_b32_e32 v125, 0xffff0000, v84
	v_lshlrev_b32_e32 v126, 16, v85
	v_and_b32_e32 v127, 0xffff0000, v85
	v_lshlrev_b32_e32 v84, 16, v86
	v_and_b32_e32 v85, 0xffff0000, v86
	v_lshlrev_b32_e32 v86, 16, v87
	v_and_b32_e32 v87, 0xffff0000, v87
	v_lshlrev_b32_e32 v131, 16, v89
	v_lshlrev_b32_e32 v130, 16, v88
	v_and_b32_e32 v175, 0xffff0000, v89
	v_and_b32_e32 v174, 0xffff0000, v88
	v_lshlrev_b32_e32 v176, 16, v96
	v_and_b32_e32 v177, 0xffff0000, v96
	v_lshlrev_b32_e32 v178, 16, v97
	v_and_b32_e32 v179, 0xffff0000, v97
	v_lshlrev_b32_e32 v133, 16, v99
	v_lshlrev_b32_e32 v132, 16, v98
	v_and_b32_e32 v181, 0xffff0000, v99
	v_and_b32_e32 v180, 0xffff0000, v98
	v_lshlrev_b32_e32 v96, 16, v158
	v_and_b32_e32 v97, 0xffff0000, v158
	v_lshlrev_b32_e32 v98, 16, v159
	v_and_b32_e32 v99, 0xffff0000, v159
	v_lshlrev_b32_e32 v158, 16, v134
	v_and_b32_e32 v159, 0xffff0000, v134
	v_lshlrev_b32_e32 v83, 16, v137
	v_lshlrev_b32_e32 v82, 16, v136
	v_and_b32_e32 v185, 0xffff0000, v137
	v_and_b32_e32 v184, 0xffff0000, v136
	v_lshlrev_b32_e32 v70, 16, v154
	v_and_b32_e32 v71, 0xffff0000, v154
	v_lshlrev_b32_e32 v74, 16, v155
	v_and_b32_e32 v75, 0xffff0000, v155
	v_lshlrev_b32_e32 v72, 16, v156
	v_and_b32_e32 v73, 0xffff0000, v156
	v_lshlrev_b32_e32 v76, 16, v157
	v_and_b32_e32 v77, 0xffff0000, v157
	v_lshlrev_b32_e32 v78, 16, v160
	v_and_b32_e32 v79, 0xffff0000, v160
	v_lshlrev_b32_e32 v80, 16, v161
	v_and_b32_e32 v81, 0xffff0000, v161
	v_lshlrev_b32_e32 v154, 16, v162
	v_and_b32_e32 v155, 0xffff0000, v162
	v_lshlrev_b32_e32 v156, 16, v163
	v_and_b32_e32 v157, 0xffff0000, v163
	v_lshlrev_b32_e32 v160, 16, v164
	v_and_b32_e32 v161, 0xffff0000, v164
	v_lshlrev_b32_e32 v162, 16, v165
	v_and_b32_e32 v163, 0xffff0000, v165
	v_pk_add_f32 v[164:165], v[170:171], -1.0 op_sel_hi:[1,0]
	v_pk_add_f32 v[170:171], v[128:129], v[172:173]
	v_lshlrev_b32_e32 v100, 16, v90
	v_and_b32_e32 v101, 0xffff0000, v90
	v_lshlrev_b32_e32 v104, 16, v91
	v_and_b32_e32 v105, 0xffff0000, v91
	v_lshlrev_b32_e32 v108, 16, v94
	v_and_b32_e32 v109, 0xffff0000, v94
	v_lshlrev_b32_e32 v110, 16, v95
	v_and_b32_e32 v111, 0xffff0000, v95
	v_lshlrev_b32_e32 v90, 16, v114
	v_and_b32_e32 v91, 0xffff0000, v114
	v_lshlrev_b32_e32 v94, 16, v115
	v_and_b32_e32 v95, 0xffff0000, v115
	v_lshlrev_b32_e32 v182, 16, v135
	v_and_b32_e32 v183, 0xffff0000, v135
	v_pk_add_f32 v[134:135], v[86:87], -1.0 op_sel_hi:[1,0]
	v_pk_add_f32 v[186:187], v[130:131], v[174:175]
	v_pk_add_f32 v[114:115], v[176:177], -1.0 op_sel_hi:[1,0]
	v_pk_add_f32 v[176:177], v[132:133], v[180:181]
	v_pk_add_f32 v[86:87], v[158:159], -1.0 op_sel_hi:[1,0]
	v_pk_add_f32 v[158:159], v[82:83], v[184:185]
	v_add_f32_e32 v141, v170, v171
	v_sub_f32_e32 v143, v143, v155
	v_sub_f32_e32 v142, v142, v154
	v_sub_f32_e32 v145, v145, v157
	v_sub_f32_e32 v144, v144, v156
	v_pk_fma_f32 v[26:27], v[26:27], v[164:165], 1.0 op_sel_hi:[1,1,0]
	v_add_f32_e32 v164, v186, v187
	v_add_f32_e32 v165, v176, v177
	v_add_f32_e32 v158, v158, v159
	v_add_f32_dpp v141, v141, v141 quad_perm:[1,0,3,2] row_mask:0xf bank_mask:0xf bound_ctrl:1
	v_lshlrev_b32_e32 v102, 16, v92
	v_and_b32_e32 v103, 0xffff0000, v92
	v_lshlrev_b32_e32 v106, 16, v93
	v_and_b32_e32 v107, 0xffff0000, v93
	v_lshlrev_b32_e32 v88, 16, v112
	v_and_b32_e32 v89, 0xffff0000, v112
	v_lshlrev_b32_e32 v92, 16, v113
	v_and_b32_e32 v93, 0xffff0000, v113
	v_pk_add_f32 v[168:169], v[168:169], -1.0 op_sel_hi:[1,0]
	v_pk_add_f32 v[112:113], v[178:179], -1.0 op_sel_hi:[1,0]
	v_lshlrev_b32_e32 v178, 16, v166
	v_and_b32_e32 v179, 0xffff0000, v166
	v_lshlrev_b32_e32 v166, 16, v167
	v_pk_fma_f32 v[14:15], v[14:15], v[144:145], v[156:157]
	v_pk_fma_f32 v[12:13], v[12:13], v[142:143], v[154:155]
	v_add_f32_dpp v154, v164, v164 quad_perm:[1,0,3,2] row_mask:0xf bank_mask:0xf bound_ctrl:1
	v_add_f32_dpp v155, v165, v165 quad_perm:[1,0,3,2] row_mask:0xf bank_mask:0xf bound_ctrl:1
	v_add_f32_dpp v156, v158, v158 quad_perm:[1,0,3,2] row_mask:0xf bank_mask:0xf bound_ctrl:1
	v_sub_f32_e32 v143, v149, v163
	v_sub_f32_e32 v142, v148, v162
	v_sub_f32_e32 v145, v147, v161
	v_sub_f32_e32 v144, v146, v160
	v_add_f32_dpp v141, v141, v141 quad_perm:[2,3,0,1] row_mask:0xf bank_mask:0xf bound_ctrl:1
	v_pk_fma_f32 v[24:25], v[24:25], v[168:169], 1.0 op_sel_hi:[1,1,0]
	v_sub_f32_e32 v146, v152, v166
	v_sub_f32_e32 v149, v151, v179
	v_sub_f32_e32 v148, v150, v178
	v_add_f32_dpp v150, v154, v154 quad_perm:[2,3,0,1] row_mask:0xf bank_mask:0xf bound_ctrl:1
	v_add_f32_dpp v151, v155, v155 quad_perm:[2,3,0,1] row_mask:0xf bank_mask:0xf bound_ctrl:1
	v_add_f32_dpp v152, v156, v156 quad_perm:[2,3,0,1] row_mask:0xf bank_mask:0xf bound_ctrl:1
	v_pk_fma_f32 v[8:9], v[8:9], v[144:145], v[160:161]
	v_pk_fma_f32 v[10:11], v[10:11], v[142:143], v[162:163]
	v_add_f32_dpp v141, v141, v141 row_half_mirror row_mask:0xf bank_mask:0xf bound_ctrl:1
	v_add_f32_dpp v142, v150, v150 row_half_mirror row_mask:0xf bank_mask:0xf bound_ctrl:1
	v_add_f32_dpp v143, v151, v151 row_half_mirror row_mask:0xf bank_mask:0xf bound_ctrl:1
	v_add_f32_dpp v144, v152, v152 row_half_mirror row_mask:0xf bank_mask:0xf bound_ctrl:1
	v_pk_mul_f32 v[10:11], v[10:11], v[26:27]
	v_pk_mul_f32 v[8:9], v[8:9], v[24:25]
	v_add_f32_dpp v24, v141, v141 row_mirror row_mask:0xf bank_mask:0xf bound_ctrl:1
	v_add_f32_dpp v25, v142, v142 row_mirror row_mask:0xf bank_mask:0xf bound_ctrl:1
	v_add_f32_dpp v26, v143, v143 row_mirror row_mask:0xf bank_mask:0xf bound_ctrl:1
	v_add_f32_dpp v27, v144, v144 row_mirror row_mask:0xf bank_mask:0xf bound_ctrl:1
	v_pk_mul_f32 v[8:9], v[12:13], v[8:9]
	v_pk_mul_f32 v[10:11], v[14:15], v[10:11]
	v_fmac_f32_e32 v172, 0xbc800000, v24
	v_fmac_f32_e32 v173, 0xbc800000, v24
	v_fmac_f32_e32 v129, 0xbc800000, v24
	v_and_b32_e32 v167, 0xffff0000, v167
	v_fmac_f32_e32 v128, 0xbc800000, v24
	v_fmac_f32_e32 v174, 0xbc800000, v25
	v_fmac_f32_e32 v175, 0xbc800000, v25
	v_fmac_f32_e32 v131, 0xbc800000, v25
	v_fmac_f32_e32 v180, 0xbc800000, v26
	v_fmac_f32_e32 v181, 0xbc800000, v26
	v_fmac_f32_e32 v133, 0xbc800000, v26
	v_fmac_f32_e32 v184, 0xbc800000, v27
	v_fmac_f32_e32 v185, 0xbc800000, v27
	v_fmac_f32_e32 v83, 0xbc800000, v27
	v_pk_mul_f32 v[10:11], v[22:23], v[10:11]
	v_pk_mul_f32 v[12:13], v[20:21], v[8:9]
	v_mov_b32_e32 v14, v129
	v_mov_b32_e32 v15, v173
	v_mov_b32_e32 v129, v172
	v_sub_f32_e32 v147, v153, v167
	v_fmac_f32_e32 v130, 0xbc800000, v25
	v_fmac_f32_e32 v132, 0xbc800000, v26
	v_fmac_f32_e32 v82, 0xbc800000, v27
	v_mov_b32_e32 v20, v131
	v_mov_b32_e32 v21, v175
	v_mov_b32_e32 v131, v174
	v_mov_b32_e32 v22, v133
	v_mov_b32_e32 v23, v181
	v_mov_b32_e32 v133, v180
	v_mov_b32_e32 v8, v83
	v_mov_b32_e32 v9, v185
	v_mov_b32_e32 v83, v184
	v_pk_mov_b32 v[24:25], v[12:13], v[10:11] op_sel:[1,0]
	v_mov_b32_e32 v13, v11
	v_pk_mul_f32 v[10:11], v[14:15], v[14:15]
	v_pk_mul_f32 v[26:27], v[128:129], v[128:129]
	v_pk_fma_f32 v[16:17], v[16:17], v[148:149], v[178:179]
	v_pk_fma_f32 v[18:19], v[18:19], v[146:147], v[166:167]
	v_pk_mul_f32 v[142:143], v[20:21], v[20:21]
	v_pk_mul_f32 v[144:145], v[130:131], v[130:131]
	v_pk_mul_f32 v[146:147], v[22:23], v[22:23]
	v_pk_mul_f32 v[148:149], v[132:133], v[132:133]
	v_pk_mul_f32 v[150:151], v[8:9], v[8:9]
	v_pk_mul_f32 v[152:153], v[82:83], v[82:83]
	v_pk_add_f32 v[12:13], v[24:25], v[12:13]
	v_pk_mov_b32 v[24:25], v[26:27], v[10:11] op_sel:[1,0]
	v_mov_b32_e32 v27, v11
	v_pk_mov_b32 v[10:11], v[144:145], v[142:143] op_sel:[1,0]
	v_mov_b32_e32 v145, v143
	v_pk_mov_b32 v[142:143], v[148:149], v[146:147] op_sel:[1,0]
	v_mov_b32_e32 v149, v147
	v_pk_mov_b32 v[146:147], v[152:153], v[150:151] op_sel:[1,0]
	v_mov_b32_e32 v153, v151
	v_add_f32_e32 v141, v12, v13
	v_pk_add_f32 v[12:13], v[24:25], v[26:27]
	v_pk_add_f32 v[10:11], v[10:11], v[144:145]
	v_pk_add_f32 v[24:25], v[142:143], v[148:149]
	v_pk_add_f32 v[26:27], v[146:147], v[152:153]
	v_add_f32_e32 v12, v12, v13
	v_add_f32_e32 v10, v10, v11
	v_add_f32_e32 v11, v24, v25
	v_add_f32_e32 v13, v26, v27
	v_add_f32_dpp v12, v12, v12 quad_perm:[1,0,3,2] row_mask:0xf bank_mask:0xf bound_ctrl:1
	v_add_f32_dpp v141, v141, v141 quad_perm:[1,0,3,2] row_mask:0xf bank_mask:0xf bound_ctrl:1
	v_add_f32_dpp v11, v11, v11 quad_perm:[1,0,3,2] row_mask:0xf bank_mask:0xf bound_ctrl:1
	v_add_f32_dpp v13, v13, v13 quad_perm:[1,0,3,2] row_mask:0xf bank_mask:0xf bound_ctrl:1
	v_add_f32_dpp v12, v12, v12 quad_perm:[2,3,0,1] row_mask:0xf bank_mask:0xf bound_ctrl:1
	v_add_f32_dpp v24, v141, v141 quad_perm:[2,3,0,1] row_mask:0xf bank_mask:0xf bound_ctrl:1
	v_add_f32_dpp v10, v10, v10 quad_perm:[1,0,3,2] row_mask:0xf bank_mask:0xf bound_ctrl:1
	v_add_f32_dpp v11, v11, v11 quad_perm:[2,3,0,1] row_mask:0xf bank_mask:0xf bound_ctrl:1
	v_add_f32_dpp v13, v13, v13 quad_perm:[2,3,0,1] row_mask:0xf bank_mask:0xf bound_ctrl:1
	v_add_f32_dpp v12, v12, v12 row_half_mirror row_mask:0xf bank_mask:0xf bound_ctrl:1
	v_add_f32_dpp v24, v24, v24 row_half_mirror row_mask:0xf bank_mask:0xf bound_ctrl:1
	v_add_f32_dpp v25, v10, v10 quad_perm:[2,3,0,1] row_mask:0xf bank_mask:0xf bound_ctrl:1
	v_add_f32_dpp v11, v11, v11 row_half_mirror row_mask:0xf bank_mask:0xf bound_ctrl:1
	v_add_f32_dpp v13, v13, v13 row_half_mirror row_mask:0xf bank_mask:0xf bound_ctrl:1
	v_add_f32_dpp v12, v12, v12 row_mirror row_mask:0xf bank_mask:0xf bound_ctrl:1
	v_add_f32_dpp v10, v24, v24 row_mirror row_mask:0xf bank_mask:0xf bound_ctrl:1
	v_add_f32_dpp v24, v25, v25 row_half_mirror row_mask:0xf bank_mask:0xf bound_ctrl:1
	v_add_f32_dpp v11, v11, v11 row_mirror row_mask:0xf bank_mask:0xf bound_ctrl:1
	v_add_f32_dpp v13, v13, v13 row_mirror row_mask:0xf bank_mask:0xf bound_ctrl:1
	v_fmamk_f32 v12, v12, 0x3c800000, v139
	v_add_f32_dpp v24, v24, v24 row_mirror row_mask:0xf bank_mask:0xf bound_ctrl:1
	v_fmamk_f32 v11, v11, 0x3c800000, v139
	v_fmamk_f32 v13, v13, 0x3c800000, v139
	v_mul_f32_e32 v25, 0x4f800000, v12
	v_cmp_gt_f32_e64 s[4:5], s28, v12
	v_fmamk_f32 v24, v24, 0x3c800000, v139
	v_mul_f32_e32 v27, 0x4f800000, v11
	v_cmp_gt_f32_e64 s[0:1], s28, v11
	v_mul_f32_e32 v141, 0x4f800000, v13
	v_cmp_gt_f32_e64 s[2:3], s28, v13
	v_cndmask_b32_e64 v12, v12, v25, s[4:5]
	v_cndmask_b32_e64 v11, v11, v27, s[0:1]
	v_cndmask_b32_e64 v141, v13, v141, s[2:3]
	v_sqrt_f32_e32 v13, v12
	v_sqrt_f32_e32 v26, v11
	v_add_u32_e32 v27, -1, v13
	v_add_u32_e32 v142, 1, v13
	v_add_u32_e32 v145, -1, v26
	v_fma_f32 v147, -v27, v13, v12
	v_add_u32_e32 v146, 1, v26
	v_fma_f32 v148, -v142, v13, v12
	v_fma_f32 v151, -v145, v26, v11
	v_cmp_ge_f32_e64 s[6:7], 0, v147
	v_fma_f32 v152, -v146, v26, v11
	s_nop 0
	v_cndmask_b32_e64 v13, v13, v27, s[6:7]
	v_cmp_ge_f32_e64 s[8:9], 0, v151
	v_cmp_lt_f32_e64 s[14:15], 0, v148
	s_nop 0
	v_cndmask_b32_e64 v26, v26, v145, s[8:9]
	v_cmp_lt_f32_e64 s[8:9], 0, v152
	v_cndmask_b32_e64 v13, v13, v142, s[14:15]
	s_nop 0
	v_cndmask_b32_e64 v26, v26, v146, s[8:9]
	v_mul_f32_e32 v27, 0x37800000, v13
	v_mul_f32_e32 v143, 0x37800000, v26
	v_cndmask_b32_e64 v13, v13, v27, s[4:5]
	v_cmp_class_f32_e64 s[4:5], v12, v140
	v_cndmask_b32_e64 v26, v26, v143, s[0:1]
	v_cmp_class_f32_e64 s[0:1], v11, v140
	v_cndmask_b32_e64 v12, v13, v12, s[4:5]
	s_nop 0
	v_cndmask_b32_e64 v11, v26, v11, s[0:1]
	v_sqrt_f32_e32 v24, v24
	s_nop 0
	v_div_scale_f32 v26, s[0:1], v24, v24, 1.0
	v_div_scale_f32 v142, s[4:5], v11, v11, 1.0
	v_rcp_f32_e32 v145, v26
	v_rcp_f32_e32 v146, v142
	v_fma_f32 v148, -v26, v145, 1.0
	v_div_scale_f32 v27, s[0:1], 1.0, v24, 1.0
	v_fma_f32 v149, -v142, v146, 1.0
	v_fmac_f32_e32 v145, v148, v145
	v_rcp_f32_e32 v12, v12
	v_div_scale_f32 v143, s[4:5], 1.0, v11, 1.0
	v_fmac_f32_e32 v146, v149, v146
	v_mul_f32_e32 v148, v27, v145
	v_pk_mul_f32 v[14:15], v[14:15], v[12:13] op_sel_hi:[1,0]
	v_pk_mul_f32 v[12:13], v[128:129], v[12:13] op_sel_hi:[1,0]
	v_mul_f32_e32 v149, v143, v146
	v_fma_f32 v151, -v26, v148, v27
	v_pk_fma_f32 v[0:1], v[0:1], v[12:13], v[4:5]
	v_pk_fma_f32 v[2:3], v[2:3], v[14:15], v[6:7]
	v_fma_f32 v152, -v142, v149, v143
	v_fmac_f32_e32 v148, v151, v145
	v_pk_fma_f32 v[2:3], v[18:19], v[10:11], v[2:3] op_sel_hi:[1,0,1]
	v_pk_fma_f32 v[0:1], v[16:17], v[10:11], v[0:1] op_sel_hi:[1,0,1]
	v_fmac_f32_e32 v149, v152, v146
	v_fma_f32 v25, -v26, v148, v27
	s_mov_b64 vcc, s[0:1]
	v_pk_mul_f32 v[0:1], v[0:1], v[116:117]
	v_pk_mul_f32 v[2:3], v[2:3], v[120:121]
	v_fma_f32 v26, -v142, v149, v143
	v_div_fmas_f32 v25, v25, v145, v148
	s_mov_b64 vcc, s[4:5]
	v_pk_fma_f32 v[2:3], v[2:3], v[122:123], v[126:127]
	v_pk_fma_f32 v[0:1], v[0:1], v[118:119], v[124:125]
	v_div_fixup_f32 v24, v25, v24, 1.0
	v_div_fmas_f32 v25, v26, v146, v149
	v_cvt_pk_bf16_f32 v0, v0, v1
	v_cvt_pk_bf16_f32 v1, v2, v3
	v_div_fixup_f32 v4, v25, v11, 1.0
	global_store_dwordx2 v[62:63], v[0:1], off
	v_pk_mul_f32 v[26:27], v[20:21], v[24:25] op_sel_hi:[1,0]
	v_pk_mul_f32 v[142:143], v[130:131], v[24:25] op_sel_hi:[1,0]
	v_pk_mul_f32 v[144:145], v[22:23], v[4:5] op_sel_hi:[1,0]
	v_pk_mul_f32 v[132:133], v[132:133], v[4:5] op_sel_hi:[1,0]
	global_load_dwordx2 v[146:147], v[64:65], off offset:512
	global_load_dwordx2 v[148:149], v[64:65], off offset:2560
	global_load_dwordx2 v[150:151], v[60:61], off offset:512
	global_load_dwordx4 v[0:3], v[36:37], off offset:1024
	global_load_dwordx4 v[4:7], v[40:41], off offset:1024
	global_load_dwordx4 v[10:13], v[42:43], off offset:1024
	global_load_dwordx4 v[14:17], v[58:59], off offset:1024
	global_load_dwordx4 v[18:21], v[66:67], off offset:1024
	global_load_dwordx4 v[22:25], v[68:69], off offset:1024
	global_load_dwordx4 v[116:119], v[30:31], off offset:1024
	global_load_dwordx4 v[120:123], v[44:45], off
	global_load_dwordx4 v[124:127], v[46:47], off
	global_load_dwordx4 v[128:131], v[38:39], off offset:1024
	v_pk_add_f32 v[136:137], v[84:85], -1.0 op_sel_hi:[1,0]
	v_sqrt_f32_e32 v158, v141
	v_pk_add_f32 v[84:85], v[182:183], -1.0 op_sel_hi:[1,0]
	v_add_u32_e32 v159, -1, v158
	v_add_u32_e32 v160, 1, v158
	v_fma_f32 v161, -v159, v158, v141
	v_cmp_ge_f32_e32 vcc, 0, v161
	s_waitcnt vmcnt(12)
	v_lshlrev_b32_e32 v152, 16, v146
	v_and_b32_e32 v153, 0xffff0000, v146
	v_lshlrev_b32_e32 v146, 16, v147
	v_and_b32_e32 v147, 0xffff0000, v147
	s_waitcnt vmcnt(11)
	v_lshlrev_b32_e32 v154, 16, v148
	v_and_b32_e32 v155, 0xffff0000, v148
	v_lshlrev_b32_e32 v148, 16, v149
	v_and_b32_e32 v149, 0xffff0000, v149
	s_waitcnt vmcnt(7)
	v_pk_fma_f32 v[4:5], v[4:5], v[142:143], v[10:11]
	v_pk_fma_f32 v[6:7], v[6:7], v[26:27], v[12:13]
	s_waitcnt vmcnt(6)
	v_sub_f32_e32 v11, v15, v153
	v_sub_f32_e32 v10, v14, v152
	v_sub_f32_e32 v13, v17, v147
	v_sub_f32_e32 v12, v16, v146
	s_waitcnt vmcnt(5)
	v_sub_f32_e32 v15, v21, v149
	v_sub_f32_e32 v14, v20, v148
	v_sub_f32_e32 v17, v19, v155
	v_sub_f32_e32 v16, v18, v154
	v_pk_fma_f32 v[0:1], v[0:1], v[136:137], 1.0 op_sel_hi:[1,1,0]
	v_pk_fma_f32 v[2:3], v[2:3], v[134:135], 1.0 op_sel_hi:[1,1,0]
	s_waitcnt vmcnt(2)
	v_pk_fma_f32 v[16:17], v[120:121], v[16:17], v[154:155]
	v_pk_fma_f32 v[14:15], v[122:123], v[14:15], v[148:149]
	v_pk_fma_f32 v[12:13], v[118:119], v[12:13], v[146:147]
	v_pk_fma_f32 v[10:11], v[116:117], v[10:11], v[152:153]
	v_pk_mul_f32 v[2:3], v[14:15], v[2:3]
	v_pk_mul_f32 v[0:1], v[16:17], v[0:1]
	v_pk_mul_f32 v[2:3], v[12:13], v[2:3]
	v_pk_mul_f32 v[0:1], v[10:11], v[0:1]
	s_waitcnt vmcnt(0)
	v_pk_mul_f32 v[2:3], v[130:131], v[2:3]
	v_pk_mul_f32 v[0:1], v[128:129], v[0:1]
	v_lshlrev_b32_e32 v156, 16, v150
	v_pk_mov_b32 v[10:11], v[0:1], v[2:3] op_sel:[1,0]
	v_mov_b32_e32 v1, v3
	v_pk_add_f32 v[0:1], v[10:11], v[0:1]
	v_and_b32_e32 v157, 0xffff0000, v150
	v_add_f32_e32 v0, v0, v1
	v_lshlrev_b32_e32 v150, 16, v151
	v_and_b32_e32 v151, 0xffff0000, v151
	v_add_f32_dpp v0, v0, v0 quad_perm:[1,0,3,2] row_mask:0xf bank_mask:0xf bound_ctrl:1
	v_sub_f32_e32 v19, v25, v151
	v_sub_f32_e32 v18, v24, v150
	v_add_f32_dpp v0, v0, v0 quad_perm:[2,3,0,1] row_mask:0xf bank_mask:0xf bound_ctrl:1
	v_sub_f32_e32 v21, v23, v157
	v_sub_f32_e32 v20, v22, v156
	v_add_f32_dpp v0, v0, v0 row_half_mirror row_mask:0xf bank_mask:0xf bound_ctrl:1
	v_pk_fma_f32 v[20:21], v[124:125], v[20:21], v[156:157]
	v_pk_fma_f32 v[18:19], v[126:127], v[18:19], v[150:151]
	v_add_f32_dpp v0, v0, v0 row_mirror row_mask:0xf bank_mask:0xf bound_ctrl:1
	v_pk_fma_f32 v[2:3], v[18:19], v[0:1], v[6:7] op_sel_hi:[1,0,1]
	v_pk_fma_f32 v[0:1], v[20:21], v[0:1], v[4:5] op_sel_hi:[1,0,1]
	v_pk_mul_f32 v[2:3], v[2:3], v[104:105]
	v_pk_mul_f32 v[0:1], v[0:1], v[100:101]
	v_pk_fma_f32 v[2:3], v[2:3], v[106:107], v[110:111]
	v_pk_fma_f32 v[0:1], v[0:1], v[102:103], v[108:109]
	s_nop 0
	v_cvt_pk_bf16_f32 v0, v0, v1
	v_cvt_pk_bf16_f32 v1, v2, v3
	global_store_dwordx2 v[62:63], v[0:1], off offset:512
	global_load_dwordx2 v[26:27], v[64:65], off offset:1024
	global_load_dwordx2 v[120:121], v[64:65], off offset:3072
	global_load_dwordx2 v[122:123], v[60:61], off offset:1024
	s_nop 0
	global_load_dwordx4 v[0:3], v[36:37], off offset:2048
	global_load_dwordx4 v[4:7], v[40:41], off offset:2048
	global_load_dwordx4 v[10:13], v[42:43], off offset:2048
	global_load_dwordx4 v[14:17], v[58:59], off offset:2048
	global_load_dwordx4 v[18:21], v[66:67], off offset:2048
	global_load_dwordx4 v[22:25], v[68:69], off offset:2048
	global_load_dwordx4 v[100:103], v[30:31], off offset:2048
	global_load_dwordx4 v[104:107], v[48:49], off
	global_load_dwordx4 v[108:111], v[50:51], off
	global_load_dwordx4 v[116:119], v[38:39], off offset:2048
	s_waitcnt vmcnt(12)
	v_lshlrev_b32_e32 v124, 16, v26
	v_and_b32_e32 v125, 0xffff0000, v26
	v_lshlrev_b32_e32 v26, 16, v27
	v_and_b32_e32 v27, 0xffff0000, v27
	s_waitcnt vmcnt(11)
	v_lshlrev_b32_e32 v126, 16, v120
	v_and_b32_e32 v127, 0xffff0000, v120
	v_lshlrev_b32_e32 v120, 16, v121
	v_and_b32_e32 v121, 0xffff0000, v121
	s_waitcnt vmcnt(7)
	v_pk_fma_f32 v[4:5], v[4:5], v[132:133], v[10:11]
	v_pk_fma_f32 v[6:7], v[6:7], v[144:145], v[12:13]
	s_waitcnt vmcnt(6)
	v_sub_f32_e32 v11, v15, v125
	v_sub_f32_e32 v10, v14, v124
	v_sub_f32_e32 v13, v17, v27
	v_sub_f32_e32 v12, v16, v26
	s_waitcnt vmcnt(5)
	v_sub_f32_e32 v15, v21, v121
	v_sub_f32_e32 v14, v20, v120
	v_sub_f32_e32 v17, v19, v127
	v_sub_f32_e32 v16, v18, v126
	v_pk_fma_f32 v[0:1], v[0:1], v[114:115], 1.0 op_sel_hi:[1,1,0]
	v_pk_fma_f32 v[2:3], v[2:3], v[112:113], 1.0 op_sel_hi:[1,1,0]
	s_waitcnt vmcnt(2)
	v_pk_fma_f32 v[16:17], v[104:105], v[16:17], v[126:127]
	v_pk_fma_f32 v[14:15], v[106:107], v[14:15], v[120:121]
	v_pk_fma_f32 v[12:13], v[102:103], v[12:13], v[26:27]
	v_pk_fma_f32 v[10:11], v[100:101], v[10:11], v[124:125]
	v_pk_mul_f32 v[2:3], v[14:15], v[2:3]
	v_pk_mul_f32 v[0:1], v[16:17], v[0:1]
	v_pk_mul_f32 v[2:3], v[12:13], v[2:3]
	v_pk_mul_f32 v[0:1], v[10:11], v[0:1]
	s_waitcnt vmcnt(0)
; template <int ph>
; __device__ __forceinline__ void run_phase(const Args& args, LAS unsigned char* lds, const int G, const int bx, const bool fin = true) {
;     ...
;         for (int row = gw; row < MP; row += ngw) {
	v_pk_mul_f32 v[2:3], v[118:119], v[2:3]
	v_pk_mul_f32 v[0:1], v[116:117], v[0:1]
	v_lshlrev_b32_e32 v128, 16, v122
	v_pk_mov_b32 v[10:11], v[0:1], v[2:3] op_sel:[1,0]
	v_mov_b32_e32 v1, v3
	v_pk_add_f32 v[0:1], v[10:11], v[0:1]
	v_and_b32_e32 v129, 0xffff0000, v122
	v_add_f32_e32 v0, v0, v1
	v_lshlrev_b32_e32 v122, 16, v123
	v_and_b32_e32 v123, 0xffff0000, v123
	v_add_f32_dpp v0, v0, v0 quad_perm:[1,0,3,2] row_mask:0xf bank_mask:0xf bound_ctrl:1
	v_sub_f32_e32 v19, v25, v123
	v_sub_f32_e32 v18, v24, v122
	v_add_f32_dpp v0, v0, v0 quad_perm:[2,3,0,1] row_mask:0xf bank_mask:0xf bound_ctrl:1
	v_sub_f32_e32 v21, v23, v129
	v_sub_f32_e32 v20, v22, v128
	v_add_f32_dpp v0, v0, v0 row_half_mirror row_mask:0xf bank_mask:0xf bound_ctrl:1
	v_pk_fma_f32 v[20:21], v[108:109], v[20:21], v[128:129]
	v_pk_fma_f32 v[18:19], v[110:111], v[18:19], v[122:123]
	v_add_f32_dpp v0, v0, v0 row_mirror row_mask:0xf bank_mask:0xf bound_ctrl:1
	v_pk_fma_f32 v[2:3], v[18:19], v[0:1], v[6:7] op_sel_hi:[1,0,1]
	v_pk_fma_f32 v[0:1], v[20:21], v[0:1], v[4:5] op_sel_hi:[1,0,1]
	v_pk_mul_f32 v[2:3], v[2:3], v[92:93]
	v_pk_mul_f32 v[0:1], v[0:1], v[88:89]
	v_pk_fma_f32 v[2:3], v[2:3], v[94:95], v[98:99]
	v_pk_fma_f32 v[0:1], v[0:1], v[90:91], v[96:97]
	s_nop 0
	v_cvt_pk_bf16_f32 v0, v0, v1
	v_cvt_pk_bf16_f32 v1, v2, v3
	global_store_dwordx2 v[62:63], v[0:1], off offset:1024
	global_load_dwordx2 v[26:27], v[64:65], off offset:1536
	global_load_dwordx2 v[104:105], v[64:65], off offset:3584
	global_load_dwordx2 v[106:107], v[60:61], off offset:1536
	s_nop 0
	global_load_dwordx4 v[0:3], v[36:37], off offset:3072
	global_load_dwordx4 v[4:7], v[40:41], off offset:3072
	global_load_dwordx4 v[10:13], v[42:43], off offset:3072
	global_load_dwordx4 v[14:17], v[58:59], off offset:3072
	global_load_dwordx4 v[18:21], v[66:67], off offset:3072
	global_load_dwordx4 v[22:25], v[68:69], off offset:3072
	global_load_dwordx4 v[88:91], v[30:31], off offset:3072
	global_load_dwordx4 v[92:95], v[52:53], off
	global_load_dwordx4 v[96:99], v[38:39], off offset:3072
	global_load_dwordx4 v[100:103], v[54:55], off
	v_fma_f32 v58, -v160, v158, v141
	v_cndmask_b32_e32 v59, v158, v159, vcc
	v_cmp_lt_f32_e32 vcc, 0, v58
	s_waitcnt vmcnt(11)
	v_lshlrev_b32_e32 v66, 16, v105
	v_cndmask_b32_e32 v58, v59, v160, vcc
	v_mul_f32_e32 v59, 0x37800000, v58
	v_cndmask_b32_e64 v58, v58, v59, s[2:3]
	v_cmp_class_f32_e32 vcc, v141, v140
	v_and_b32_e32 v67, 0xffff0000, v105
	s_waitcnt vmcnt(9)
	v_pk_fma_f32 v[0:1], v[0:1], v[86:87], 1.0 op_sel_hi:[1,1,0]
	v_cndmask_b32_e32 v58, v58, v141, vcc
	v_pk_fma_f32 v[2:3], v[2:3], v[84:85], 1.0 op_sel_hi:[1,1,0]
	v_rcp_f32_e32 v58, v58
	s_nop 0
	v_pk_mul_f32 v[8:9], v[8:9], v[58:59] op_sel_hi:[1,0]
	v_lshlrev_b32_e32 v60, 16, v26
	v_and_b32_e32 v61, 0xffff0000, v26
	v_lshlrev_b32_e32 v64, 16, v104
	v_and_b32_e32 v65, 0xffff0000, v104
	v_pk_mul_f32 v[58:59], v[82:83], v[58:59] op_sel_hi:[1,0]
	v_lshlrev_b32_e32 v26, 16, v27
	v_and_b32_e32 v27, 0xffff0000, v27
	s_waitcnt vmcnt(7)
	v_pk_fma_f32 v[6:7], v[6:7], v[8:9], v[12:13]
	s_waitcnt vmcnt(6)
	v_sub_f32_e32 v9, v15, v61
	v_sub_f32_e32 v8, v14, v60
	s_waitcnt vmcnt(5)
	v_sub_f32_e32 v13, v21, v67
	v_sub_f32_e32 v12, v20, v66
	v_sub_f32_e32 v15, v19, v65
	v_sub_f32_e32 v14, v18, v64
	v_pk_fma_f32 v[4:5], v[4:5], v[58:59], v[10:11]
	v_sub_f32_e32 v11, v17, v27
	v_sub_f32_e32 v10, v16, v26
	s_waitcnt vmcnt(2)
	v_pk_fma_f32 v[14:15], v[92:93], v[14:15], v[64:65]
	v_pk_fma_f32 v[12:13], v[94:95], v[12:13], v[66:67]
	v_pk_fma_f32 v[10:11], v[90:91], v[10:11], v[26:27]
	v_pk_fma_f32 v[8:9], v[88:89], v[8:9], v[60:61]
	v_pk_mul_f32 v[2:3], v[12:13], v[2:3]
	v_pk_mul_f32 v[0:1], v[14:15], v[0:1]
	v_pk_mul_f32 v[2:3], v[10:11], v[2:3]
	v_pk_mul_f32 v[0:1], v[8:9], v[0:1]
	s_waitcnt vmcnt(1)
	v_pk_mul_f32 v[2:3], v[98:99], v[2:3]
	v_pk_mul_f32 v[0:1], v[96:97], v[0:1]
	v_lshlrev_b32_e32 v68, 16, v106
	v_pk_mov_b32 v[8:9], v[0:1], v[2:3] op_sel:[1,0]
	v_mov_b32_e32 v1, v3
	v_pk_add_f32 v[0:1], v[8:9], v[0:1]
	v_and_b32_e32 v69, 0xffff0000, v106
	v_add_f32_e32 v0, v0, v1
	v_lshlrev_b32_e32 v82, 16, v107
	v_and_b32_e32 v83, 0xffff0000, v107
	v_add_f32_dpp v0, v0, v0 quad_perm:[1,0,3,2] row_mask:0xf bank_mask:0xf bound_ctrl:1
	v_sub_f32_e32 v17, v25, v83
	v_sub_f32_e32 v16, v24, v82
	v_add_f32_dpp v0, v0, v0 quad_perm:[2,3,0,1] row_mask:0xf bank_mask:0xf bound_ctrl:1
	v_sub_f32_e32 v19, v23, v69
	v_sub_f32_e32 v18, v22, v68
	v_add_f32_dpp v0, v0, v0 row_half_mirror row_mask:0xf bank_mask:0xf bound_ctrl:1
	s_waitcnt vmcnt(0)
	v_pk_fma_f32 v[18:19], v[100:101], v[18:19], v[68:69]
	v_pk_fma_f32 v[16:17], v[102:103], v[16:17], v[82:83]
	v_add_f32_dpp v0, v0, v0 row_mirror row_mask:0xf bank_mask:0xf bound_ctrl:1
	v_pk_fma_f32 v[2:3], v[16:17], v[0:1], v[6:7] op_sel_hi:[1,0,1]
	v_pk_fma_f32 v[0:1], v[18:19], v[0:1], v[4:5] op_sel_hi:[1,0,1]
	v_pk_mul_f32 v[2:3], v[2:3], v[74:75]
	v_pk_mul_f32 v[0:1], v[0:1], v[70:71]
	v_pk_fma_f32 v[2:3], v[2:3], v[76:77], v[80:81]
	v_pk_fma_f32 v[0:1], v[0:1], v[72:73], v[78:79]
	s_nop 0
	v_cvt_pk_bf16_f32 v0, v0, v1
	v_cvt_pk_bf16_f32 v1, v2, v3
	global_store_dwordx2 v[62:63], v[0:1], off offset:1536
	s_cbranch_scc1 .LBB0_1143
